# attention K-fragment read bases derived by XOR from the first base (6 fewer VALU per step) on top of the early tile barrier
# speedup vs baseline: 1.0014x; 1.0014x over previous
.LBB0_185:
	v_mbcnt_lo_u32_b32 v192, -1, 0
	v_mbcnt_hi_u32_b32 v192, -1, v192
	s_add_i32 s35, 0, 0x10000
	s_add_i32 s37, s35, s61
	s_add_i32 s92, s37, 0x4000
	s_add_i32 s35, s35, s65
	s_add_i32 s93, s35, 0x4000
	s_add_u32 s98, s8, s14
	s_addc_u32 s99, s9, s15
	s_add_u32 s100, s8, s28
	s_addc_u32 s101, s9, s29
	s_add_i32 s36, s68, s79
	s_add_i32 s90, s36, 64
	s_add_i32 s34, s79, 63
	s_mul_hi_i32 s91, s90, 0xa000
	s_mul_i32 s90, s90, 0xa000
	s_add_u32 s90, s82, s90
	s_addc_u32 s91, s83, s91
	s_add_i32 s94, s47, s70
	s_add_i32 s95, s94, 0x380
	s_add_i32 s96, s47, s74
	s_add_i32 s97, s47, s77
	s_addk_i32 s97, 0xff80
	v_ashrrev_i32_e32 v188, 5, v192
	v_and_b32_e32 v193, 31, v192
	v_lshlrev_b32_e32 v189, 4, v192
	v_lshlrev_b32_e32 v191, 4, v188
	v_lshlrev_b32_e32 v190, 8, v193
	v_bitop3_b32 v2, v189, v191, s48 bitop3:0x6c
	v_add3_u32 v6, s84, v2, v190
	v_xor_b32_e32 v250, 32, v6
	v_xor_b32_e32 v222, 64, v6
	v_xor_b32_e32 v190, 0x60, v6
	v_add_u32_e32 v189, s81, v189
	ds_read_b128 v[2:5], v6
	ds_read_b128 v[194:197], v6 offset:8192
	ds_read_b128 v[198:201], v250
	ds_read_b128 v[202:205], v250 offset:8192
	ds_read_b128 v[206:209], v222
	ds_read_b128 v[210:213], v222 offset:8192
	ds_read_b128 v[214:217], v190
	ds_read_b128 v[218:221], v190 offset:8192
	ds_read_b128 v[226:229], v6 offset:128
	ds_read_b128 v[230:233], v6 offset:8320
	s_waitcnt lgkmcnt(9)
	s_mov_b32 m0, s37
	v_mfma_f32_32x32x16_bf16 v[18:33], v[2:5], v[34:37], 0
	global_load_lds_dwordx4 v251, s[98:99]
	s_waitcnt lgkmcnt(8)
	s_mov_b32 m0, s92
	v_mfma_f32_32x32x16_bf16 v[2:17], v[194:197], v[34:37], 0
	global_load_lds_dwordx4 v251, s[100:101]
	ds_read_b128 v[194:197], v250 offset:128
	s_waitcnt lgkmcnt(8)
	s_mov_b32 m0, s35
	v_mfma_f32_32x32x16_bf16 v[18:33], v[198:201], v[38:41], v[18:33]
	global_load_lds_dwordx4 v252, s[98:99]
	ds_read_b128 v[198:201], v250 offset:8320
	s_waitcnt lgkmcnt(8)
	s_mov_b32 m0, s93
	v_mfma_f32_32x32x16_bf16 v[2:17], v[202:205], v[38:41], v[2:17]
	global_load_lds_dwordx4 v252, s[100:101]
	ds_read_b128 v[202:205], v222 offset:128
	s_waitcnt lgkmcnt(8)
	s_mov_b32 m0, s94
	v_mfma_f32_32x32x16_bf16 v[18:33], v[206:209], v[42:45], v[18:33]
	global_load_lds_dwordx4 v253, s[90:91]
	ds_read_b128 v[206:209], v222 offset:8320
	s_waitcnt lgkmcnt(8)
	s_mov_b32 m0, s95
	v_mfma_f32_32x32x16_bf16 v[2:17], v[210:213], v[42:45], v[2:17]
	global_load_lds_dwordx4 v253, s[90:91] offset:128
	ds_read_b128 v[210:213], v190 offset:128
	s_waitcnt lgkmcnt(8)
	s_mov_b32 m0, s96
	v_mfma_f32_32x32x16_bf16 v[18:33], v[214:217], v[46:49], v[18:33]
	global_load_lds_dwordx4 v254, s[90:91]
	ds_read_b128 v[214:217], v190 offset:8320
	s_waitcnt lgkmcnt(8)
	s_mov_b32 m0, s97
	v_mfma_f32_32x32x16_bf16 v[2:17], v[218:221], v[46:49], v[2:17]
	global_load_lds_dwordx4 v254, s[90:91] offset:128
	ds_read_b128 v[218:221], v189
	s_waitcnt lgkmcnt(8)
	v_mfma_f32_32x32x16_bf16 v[18:33], v[226:229], v[50:53], v[18:33]
	ds_read_b128 v[226:229], v189 offset:1024
	s_waitcnt lgkmcnt(8)
	v_mfma_f32_32x32x16_bf16 v[2:17], v[230:233], v[50:53], v[2:17]
	s_waitcnt lgkmcnt(7)
	v_mfma_f32_32x32x16_bf16 v[18:33], v[194:197], v[54:57], v[18:33]
	s_waitcnt lgkmcnt(6)
	v_mfma_f32_32x32x16_bf16 v[2:17], v[198:201], v[54:57], v[2:17]
	s_waitcnt lgkmcnt(1)
	v_mfma_f32_32x32x16_bf16 v[18:33], v[202:205], v[218:221], v[18:33]
	v_mfma_f32_32x32x16_bf16 v[2:17], v[206:209], v[218:221], v[2:17]
	s_waitcnt lgkmcnt(0)
	v_mfma_f32_32x32x16_bf16 v[18:33], v[210:213], v[226:229], v[18:33]
	s_cmp_le_u32 s34, s59
	v_mfma_f32_32x32x16_bf16 v[2:17], v[214:217], v[226:229], v[2:17]
	s_cbranch_scc1 .LBB0_187
	v_lshlrev_b32_e32 v188, 2, v188
	v_sub_u32_e32 v188, v193, v188
	v_add_u32_e32 v188, s86, v188
	v_add_u32_e32 v189, 0x80000001, v188
	v_cmp_gt_u32_e32 vcc, s46, v189
	s_nop 4
	v_cndmask_b32_e32 v18, v225, v18, vcc
	v_cmp_lt_i32_e32 vcc, 31, v189
	s_nop 1
	v_cndmask_b32_e32 v2, v225, v2, vcc
	v_cmp_lt_i32_e32 vcc, 0, v189
	v_subrev_u32_e32 v189, 31, v188
	s_nop 0
	v_cndmask_b32_e32 v19, v225, v19, vcc
	v_cmp_lt_u32_e32 vcc, s49, v189
	v_subrev_u32_e32 v189, 32, v188
	s_nop 0
	v_cndmask_b32_e32 v3, v225, v3, vcc
	v_cmp_lt_u32_e32 vcc, s49, v188
	s_nop 1
	v_cndmask_b32_e32 v20, v225, v20, vcc
	v_cmp_lt_u32_e32 vcc, s49, v189
	v_add_u32_e32 v189, -1, v188
	s_nop 0
	v_cndmask_b32_e32 v4, v225, v4, vcc
	v_cmp_lt_u32_e32 vcc, s49, v189
	v_subrev_u32_e32 v189, 33, v188
	s_nop 0
	v_cndmask_b32_e32 v21, v225, v21, vcc
	v_cmp_lt_u32_e32 vcc, s49, v189
	v_add_u32_e32 v189, -6, v188
	s_nop 0
	v_cndmask_b32_e32 v5, v225, v5, vcc
	v_cmp_lt_u32_e32 vcc, s49, v189
	v_subrev_u32_e32 v189, 38, v188
	s_nop 0
	v_cndmask_b32_e32 v22, v225, v22, vcc
	v_cmp_lt_u32_e32 vcc, s49, v189
	v_add_u32_e32 v189, -7, v188
	s_nop 0
	v_cndmask_b32_e32 v6, v225, v6, vcc
	v_cmp_lt_u32_e32 vcc, s49, v189
	v_subrev_u32_e32 v189, 39, v188
	s_nop 0
	v_cndmask_b32_e32 v23, v225, v23, vcc
	v_cmp_lt_u32_e32 vcc, s49, v189
	v_add_u32_e32 v189, -8, v188
	s_nop 0
	v_cndmask_b32_e32 v7, v225, v7, vcc
	v_cmp_lt_u32_e32 vcc, s49, v189
	v_subrev_u32_e32 v189, 40, v188
	s_nop 0
	v_cndmask_b32_e32 v24, v225, v24, vcc
	v_cmp_lt_u32_e32 vcc, s49, v189
	v_add_u32_e32 v189, -9, v188
	s_nop 0
	v_cndmask_b32_e32 v8, v225, v8, vcc
	v_cmp_lt_u32_e32 vcc, s49, v189
	v_subrev_u32_e32 v189, 41, v188
	s_nop 0
	v_cndmask_b32_e32 v25, v225, v25, vcc
	v_cmp_lt_u32_e32 vcc, s49, v189
	v_add_u32_e32 v189, -14, v188
	s_nop 0
	v_cndmask_b32_e32 v9, v225, v9, vcc
	v_cmp_lt_u32_e32 vcc, s49, v189
	v_subrev_u32_e32 v189, 46, v188
	s_nop 0
	v_cndmask_b32_e32 v26, v225, v26, vcc
	v_cmp_lt_u32_e32 vcc, s49, v189
	v_add_u32_e32 v189, -15, v188
	s_nop 0
	v_cndmask_b32_e32 v10, v225, v10, vcc
	v_cmp_lt_u32_e32 vcc, s49, v189
	v_subrev_u32_e32 v189, 47, v188
	s_nop 0
	v_cndmask_b32_e32 v27, v225, v27, vcc
	v_cmp_lt_u32_e32 vcc, s49, v189
	v_add_u32_e32 v189, -16, v188
	s_nop 0
	v_cndmask_b32_e32 v11, v225, v11, vcc
	v_cmp_lt_u32_e32 vcc, s49, v189
	v_subrev_u32_e32 v189, 48, v188
	s_nop 0
	v_cndmask_b32_e32 v28, v225, v28, vcc
	v_cmp_lt_u32_e32 vcc, s49, v189
	v_subrev_u32_e32 v189, 17, v188
	s_nop 0
	v_cndmask_b32_e32 v12, v225, v12, vcc
	v_cmp_lt_u32_e32 vcc, s49, v189
	v_subrev_u32_e32 v189, 49, v188
	s_nop 0
	v_cndmask_b32_e32 v29, v225, v29, vcc
	v_cmp_lt_u32_e32 vcc, s49, v189
	v_subrev_u32_e32 v189, 22, v188
	s_nop 0
	v_cndmask_b32_e32 v13, v225, v13, vcc
	v_cmp_lt_u32_e32 vcc, s49, v189
	v_subrev_u32_e32 v189, 54, v188
	s_nop 0
	v_cndmask_b32_e32 v30, v225, v30, vcc
	v_cmp_lt_u32_e32 vcc, s49, v189
	v_subrev_u32_e32 v189, 23, v188
	s_nop 0
	v_cndmask_b32_e32 v14, v225, v14, vcc
	v_cmp_lt_u32_e32 vcc, s49, v189
	v_subrev_u32_e32 v189, 55, v188
	s_nop 0
	v_cndmask_b32_e32 v31, v225, v31, vcc
	v_cmp_lt_u32_e32 vcc, s49, v189
	v_subrev_u32_e32 v189, 24, v188
	s_nop 0
	v_cndmask_b32_e32 v15, v225, v15, vcc
	v_cmp_lt_u32_e32 vcc, s49, v189
	v_subrev_u32_e32 v189, 56, v188
	s_nop 0
	v_cndmask_b32_e32 v32, v225, v32, vcc
	v_cmp_lt_u32_e32 vcc, s49, v189
	v_subrev_u32_e32 v189, 25, v188
	v_subrev_u32_e32 v188, 57, v188
	v_cndmask_b32_e32 v16, v225, v16, vcc
	v_cmp_lt_u32_e32 vcc, s49, v189
	s_nop 1
	v_cndmask_b32_e32 v33, v225, v33, vcc
	v_cmp_lt_u32_e32 vcc, s49, v188
	s_nop 1
	v_cndmask_b32_e32 v17, v225, v17, vcc

.LBB0_192:
	s_cmp_lg_u32 0, -1
	s_cselect_b32 s34, 0, 0
	s_add_i32 s34, s34, 0x8000
	s_waitcnt lgkmcnt(0)
	v_add_u32_e32 v220, s34, v255
	v_xor_b32_e32 v221, 0x110, v220
	ds_read_b64_tr_b16 v[18:19], v220 offset:0
	ds_read_b64_tr_b16 v[20:21], v221 offset:0
	v_xor_b32_e32 v222, 32, v220
	ds_read_b64_tr_b16 v[22:23], v222 offset:0
	v_xor_b32_e32 v250, 32, v221
	ds_read_b64_tr_b16 v[24:25], v250 offset:0
	ds_read_b64_tr_b16 v[26:27], v220 offset:0x200
	ds_read_b64_tr_b16 v[28:29], v221 offset:0x200
	s_waitcnt lgkmcnt(4)
	v_permlane16_swap_b32_e32 v10, v14
	v_permlane16_swap_b32_e32 v11, v15
	v_permlane16_swap_b32_e32 v12, v16
	v_permlane16_swap_b32_e32 v13, v17
	v_permlane16_swap_b32_e32 v2, v6
	v_permlane16_swap_b32_e32 v3, v7
	v_permlane16_swap_b32_e32 v4, v8
	v_permlane16_swap_b32_e32 v5, v9
	v_mfma_f32_16x16x32_bf16 v[30:33], v[10:13], v[18:21], v[58:61]
	v_mfma_f32_16x16x32_bf16 v[18:21], v[14:17], v[18:21], v[178:181]
	ds_read_b64_tr_b16 v[58:59], v222 offset:0x200
	ds_read_b64_tr_b16 v[60:61], v250 offset:0x200
	s_waitcnt lgkmcnt(4)
	v_mfma_f32_16x16x32_bf16 v[62:65], v[10:13], v[22:25], v[62:65]
	v_mfma_f32_16x16x32_bf16 v[22:25], v[14:17], v[22:25], v[166:169]
	ds_read_b64_tr_b16 v[166:167], v220 offset:0x400
	ds_read_b64_tr_b16 v[168:169], v221 offset:0x400
	s_waitcnt lgkmcnt(4)
	v_mfma_f32_16x16x32_bf16 v[66:69], v[10:13], v[26:29], v[66:69]
	v_mfma_f32_16x16x32_bf16 v[26:29], v[14:17], v[26:29], v[162:165]
	ds_read_b64_tr_b16 v[162:163], v222 offset:0x400
	ds_read_b64_tr_b16 v[164:165], v250 offset:0x400
	s_waitcnt lgkmcnt(4)
	v_mfma_f32_16x16x32_bf16 v[70:73], v[10:13], v[58:61], v[70:73]
	v_mfma_f32_16x16x32_bf16 v[58:61], v[14:17], v[58:61], v[154:157]
	ds_read_b64_tr_b16 v[154:155], v220 offset:0x600
	ds_read_b64_tr_b16 v[156:157], v221 offset:0x600
	s_waitcnt lgkmcnt(4)
	v_mfma_f32_16x16x32_bf16 v[178:181], v[10:13], v[166:169], v[74:77]
	v_mfma_f32_16x16x32_bf16 v[150:153], v[14:17], v[166:169], v[150:153]
	ds_read_b64_tr_b16 v[74:75], v222 offset:0x600
	ds_read_b64_tr_b16 v[76:77], v250 offset:0x600
	s_waitcnt lgkmcnt(4)
	v_mfma_f32_16x16x32_bf16 v[166:169], v[10:13], v[162:165], v[82:85]
	v_mfma_f32_16x16x32_bf16 v[162:165], v[14:17], v[162:165], v[142:145]
	ds_read_b64_tr_b16 v[82:83], v220 offset:0x2000
	ds_read_b64_tr_b16 v[84:85], v221 offset:0x2000
	s_waitcnt lgkmcnt(4)
	v_mfma_f32_16x16x32_bf16 v[192:195], v[10:13], v[154:157], v[90:93]
	v_mfma_f32_16x16x32_bf16 v[154:157], v[14:17], v[154:157], v[138:141]
	ds_read_b64_tr_b16 v[90:91], v222 offset:0x2000
	ds_read_b64_tr_b16 v[92:93], v250 offset:0x2000
	s_waitcnt lgkmcnt(4)
	v_mfma_f32_16x16x32_bf16 v[196:199], v[10:13], v[74:77], v[98:101]
	v_mfma_f32_16x16x32_bf16 v[200:203], v[14:17], v[74:77], v[130:133]
	ds_read_b64_tr_b16 v[74:75], v220 offset:0x2200
	ds_read_b64_tr_b16 v[76:77], v221 offset:0x2200
	s_waitcnt lgkmcnt(4)
	v_mfma_f32_16x16x32_bf16 v[110:113], v[10:13], v[82:85], v[110:113]
	v_mfma_f32_16x16x32_bf16 v[126:129], v[14:17], v[82:85], v[126:129]
	ds_read_b64_tr_b16 v[82:83], v222 offset:0x2200
	ds_read_b64_tr_b16 v[84:85], v250 offset:0x2200
	s_waitcnt lgkmcnt(4)
	v_mfma_f32_16x16x32_bf16 v[122:125], v[10:13], v[90:93], v[122:125]
	v_mfma_f32_16x16x32_bf16 v[118:121], v[14:17], v[90:93], v[118:121]
	ds_read_b64_tr_b16 v[90:91], v220 offset:0x2400
	ds_read_b64_tr_b16 v[92:93], v221 offset:0x2400
	s_waitcnt lgkmcnt(4)
	v_mfma_f32_16x16x32_bf16 v[204:207], v[10:13], v[74:77], v[134:137]
	v_mfma_f32_16x16x32_bf16 v[208:211], v[14:17], v[74:77], v[114:117]
	ds_read_b64_tr_b16 v[74:75], v222 offset:0x2400
	ds_read_b64_tr_b16 v[76:77], v250 offset:0x2400
	s_waitcnt lgkmcnt(4)
	v_mfma_f32_16x16x32_bf16 v[212:215], v[10:13], v[82:85], v[146:149]
	v_mfma_f32_16x16x32_bf16 v[216:219], v[14:17], v[82:85], v[106:109]
	ds_read_b64_tr_b16 v[82:83], v220 offset:0x2600
	ds_read_b64_tr_b16 v[84:85], v221 offset:0x2600
	s_waitcnt lgkmcnt(4)
	v_mfma_f32_16x16x32_bf16 v[226:229], v[10:13], v[90:93], v[158:161]
	v_mfma_f32_16x16x32_bf16 v[230:233], v[14:17], v[90:93], v[102:105]
	ds_read_b64_tr_b16 v[90:91], v222 offset:0x2600
	ds_read_b64_tr_b16 v[92:93], v250 offset:0x2600
	s_waitcnt lgkmcnt(4)
	v_mfma_f32_16x16x32_bf16 v[234:237], v[10:13], v[74:77], v[174:177]
	v_mfma_f32_16x16x32_bf16 v[238:241], v[14:17], v[74:77], v[94:97]
	ds_read_b64_tr_b16 v[94:95], v220 offset:0x4000
	ds_read_b64_tr_b16 v[96:97], v221 offset:0x4000
	s_waitcnt lgkmcnt(4)
	v_mfma_f32_16x16x32_bf16 v[242:245], v[10:13], v[82:85], v[182:185]
	v_mfma_f32_16x16x32_bf16 v[246:249], v[14:17], v[82:85], v[86:89]
	ds_read_b64_tr_b16 v[82:83], v222 offset:0x4000
	ds_read_b64_tr_b16 v[84:85], v250 offset:0x4000
	s_waitcnt lgkmcnt(4)
	v_mfma_f32_16x16x32_bf16 v[10:13], v[10:13], v[90:93], v[170:173]
	v_mfma_f32_16x16x32_bf16 v[14:17], v[14:17], v[90:93], v[78:81]
	ds_read_b64_tr_b16 v[86:87], v220 offset:0x4200
	ds_read_b64_tr_b16 v[88:89], v221 offset:0x4200
	s_waitcnt lgkmcnt(4)
	v_mfma_f32_16x16x32_bf16 v[74:77], v[2:5], v[94:97], v[30:33]
	v_mfma_f32_16x16x32_bf16 v[130:133], v[6:9], v[94:97], v[18:21]
	ds_read_b64_tr_b16 v[18:19], v222 offset:0x4200
	ds_read_b64_tr_b16 v[20:21], v250 offset:0x4200
	s_waitcnt lgkmcnt(4)
	v_mfma_f32_16x16x32_bf16 v[78:81], v[2:5], v[82:85], v[62:65]
	v_mfma_f32_16x16x32_bf16 v[134:137], v[6:9], v[82:85], v[22:25]
	ds_read_b64_tr_b16 v[22:23], v220 offset:0x4400
	ds_read_b64_tr_b16 v[24:25], v221 offset:0x4400
	s_waitcnt lgkmcnt(4)
	v_mfma_f32_16x16x32_bf16 v[82:85], v[2:5], v[86:89], v[66:69]
	v_mfma_f32_16x16x32_bf16 v[138:141], v[6:9], v[86:89], v[26:29]
	ds_read_b64_tr_b16 v[26:27], v222 offset:0x4400
	ds_read_b64_tr_b16 v[28:29], v250 offset:0x4400
	s_waitcnt lgkmcnt(4)
	v_mfma_f32_16x16x32_bf16 v[86:89], v[2:5], v[18:21], v[70:73]
	v_mfma_f32_16x16x32_bf16 v[142:145], v[6:9], v[18:21], v[58:61]
	ds_read_b64_tr_b16 v[18:19], v220 offset:0x4600
	ds_read_b64_tr_b16 v[20:21], v221 offset:0x4600
	s_waitcnt lgkmcnt(4)
	v_mfma_f32_16x16x32_bf16 v[90:93], v[2:5], v[22:25], v[178:181]
	v_mfma_f32_16x16x32_bf16 v[146:149], v[6:9], v[22:25], v[150:153]
	ds_read_b64_tr_b16 v[22:23], v222 offset:0x4600
	ds_read_b64_tr_b16 v[24:25], v250 offset:0x4600
	s_waitcnt lgkmcnt(4)
	v_mfma_f32_16x16x32_bf16 v[94:97], v[2:5], v[26:29], v[166:169]
	v_mfma_f32_16x16x32_bf16 v[150:153], v[6:9], v[26:29], v[162:165]
	ds_read_b64_tr_b16 v[26:27], v220 offset:0x6000
	ds_read_b64_tr_b16 v[28:29], v221 offset:0x6000
	s_waitcnt lgkmcnt(4)
	v_mfma_f32_16x16x32_bf16 v[98:101], v[2:5], v[18:21], v[192:195]
	v_mfma_f32_16x16x32_bf16 v[154:157], v[6:9], v[18:21], v[154:157]
	ds_read_b64_tr_b16 v[18:19], v222 offset:0x6000
	ds_read_b64_tr_b16 v[20:21], v250 offset:0x6000
	s_waitcnt lgkmcnt(4)
	v_mfma_f32_16x16x32_bf16 v[102:105], v[2:5], v[22:25], v[196:199]
	v_mfma_f32_16x16x32_bf16 v[158:161], v[6:9], v[22:25], v[200:203]
	ds_read_b64_tr_b16 v[22:23], v220 offset:0x6200
	ds_read_b64_tr_b16 v[24:25], v221 offset:0x6200
	s_waitcnt lgkmcnt(4)
	v_mfma_f32_16x16x32_bf16 v[106:109], v[2:5], v[26:29], v[110:113]
	v_mfma_f32_16x16x32_bf16 v[162:165], v[6:9], v[26:29], v[126:129]
	ds_read_b64_tr_b16 v[26:27], v222 offset:0x6200
	ds_read_b64_tr_b16 v[28:29], v250 offset:0x6200
	s_waitcnt lgkmcnt(4)
	v_mfma_f32_16x16x32_bf16 v[110:113], v[2:5], v[18:21], v[122:125]
	v_mfma_f32_16x16x32_bf16 v[166:169], v[6:9], v[18:21], v[118:121]
	ds_read_b64_tr_b16 v[18:19], v220 offset:0x6400
	ds_read_b64_tr_b16 v[20:21], v221 offset:0x6400
	s_waitcnt lgkmcnt(4)
	v_mfma_f32_16x16x32_bf16 v[114:117], v[2:5], v[22:25], v[204:207]
	v_mfma_f32_16x16x32_bf16 v[170:173], v[6:9], v[22:25], v[208:211]
	ds_read_b64_tr_b16 v[22:23], v222 offset:0x6400
	ds_read_b64_tr_b16 v[24:25], v250 offset:0x6400
	s_waitcnt lgkmcnt(4)
	v_mfma_f32_16x16x32_bf16 v[118:121], v[2:5], v[26:29], v[212:215]
	v_mfma_f32_16x16x32_bf16 v[174:177], v[6:9], v[26:29], v[216:219]
	ds_read_b64_tr_b16 v[26:27], v220 offset:0x6600
	ds_read_b64_tr_b16 v[28:29], v221 offset:0x6600
	s_waitcnt lgkmcnt(4)
	v_mfma_f32_16x16x32_bf16 v[122:125], v[2:5], v[18:21], v[226:229]
	v_mfma_f32_16x16x32_bf16 v[178:181], v[6:9], v[18:21], v[230:233]
	ds_read_b64_tr_b16 v[18:19], v222 offset:0x6600
	ds_read_b64_tr_b16 v[20:21], v250 offset:0x6600
	s_waitcnt lgkmcnt(4)
	v_mfma_f32_16x16x32_bf16 v[126:129], v[2:5], v[22:25], v[234:237]
	v_mfma_f32_16x16x32_bf16 v[182:185], v[6:9], v[22:25], v[238:241]
	s_waitcnt lgkmcnt(2)
	v_mfma_f32_16x16x32_bf16 v[66:69], v[2:5], v[26:29], v[242:245]
	v_mfma_f32_16x16x32_bf16 v[70:73], v[6:9], v[26:29], v[246:249]
	s_waitcnt lgkmcnt(0)
	s_waitcnt vmcnt(0)
	s_barrier
	v_mfma_f32_16x16x32_bf16 v[58:61], v[2:5], v[18:21], v[10:13]
	v_mfma_f32_16x16x32_bf16 v[62:65], v[6:9], v[18:21], v[14:17]
	s_cmp_ge_u32 s89, s80
	s_cselect_b64 s[34:35], -1, 0
	s_and_b64 vcc, exec, s[34:35]
	v_mbcnt_lo_u32_b32 v192, -1, 0
	v_mbcnt_hi_u32_b32 v192, -1, v192
	s_cbranch_vccnz .LBB0_194
	s_add_u32 s98, s8, s30
	s_addc_u32 s99, s9, s31
	s_addk_i32 s36, 0x80
	s_mul_hi_i32 s37, s36, 0xa000
	s_mul_i32 s36, s36, 0xa000
	s_add_u32 s36, s82, s36
	s_addc_u32 s37, s83, s37
	s_add_i32 s100, s72, 0xffffff80
	s_add_i32 s101, s78, 0xffffff80
	v_ashrrev_i32_e32 v193, 5, v192
	v_and_b32_e32 v194, 31, v192
	v_lshlrev_b32_e32 v195, 4, v192
	v_lshlrev_b32_e32 v221, 4, v193
	v_lshlrev_b32_e32 v220, 8, v194
	v_bitop3_b32 v2, v195, v221, s48 bitop3:0x6c
	v_add3_u32 v6, s85, v2, v220
	v_xor_b32_e32 v250, 32, v6
	v_xor_b32_e32 v222, 64, v6
	v_xor_b32_e32 v220, 0x60, v6
	v_add_u32_e32 v195, s81, v195
	ds_read_b128 v[2:5], v6
	ds_read_b128 v[196:199], v6 offset:8192
	ds_read_b128 v[200:203], v250
	ds_read_b128 v[204:207], v250 offset:8192
	ds_read_b128 v[208:211], v222
	ds_read_b128 v[212:215], v222 offset:8192
	ds_read_b128 v[216:219], v220
	ds_read_b128 v[226:229], v220 offset:8192
	ds_read_b128 v[230:233], v6 offset:128
	ds_read_b128 v[234:237], v6 offset:8320
	s_waitcnt lgkmcnt(9)
	s_mov_b32 m0, s62
	v_mfma_f32_32x32x16_bf16 v[18:33], v[2:5], v[34:37], 0
	global_load_lds_dwordx4 v251, s[98:99]
	s_waitcnt lgkmcnt(8)
	s_mov_b32 m0, s63
	v_mfma_f32_32x32x16_bf16 v[2:17], v[196:199], v[34:37], 0
	global_load_lds_dwordx4 v251, s[8:9]
	ds_read_b128 v[196:199], v250 offset:128
	s_waitcnt lgkmcnt(8)
	s_mov_b32 m0, s66
	v_mfma_f32_32x32x16_bf16 v[18:33], v[200:203], v[38:41], v[18:33]
	global_load_lds_dwordx4 v252, s[98:99]
	ds_read_b128 v[200:203], v250 offset:8320
	s_waitcnt lgkmcnt(8)
	s_mov_b32 m0, s67
	v_mfma_f32_32x32x16_bf16 v[2:17], v[204:207], v[38:41], v[2:17]
	global_load_lds_dwordx4 v252, s[8:9]
	ds_read_b128 v[204:207], v222 offset:128
	s_waitcnt lgkmcnt(8)
	s_mov_b32 m0, s71
	v_mfma_f32_32x32x16_bf16 v[18:33], v[208:211], v[42:45], v[18:33]
	global_load_lds_dwordx4 v253, s[36:37]
	ds_read_b128 v[208:211], v222 offset:8320
	s_waitcnt lgkmcnt(8)
	s_mov_b32 m0, s100
	v_mfma_f32_32x32x16_bf16 v[2:17], v[212:215], v[42:45], v[2:17]
	global_load_lds_dwordx4 v253, s[36:37] offset:128
	ds_read_b128 v[212:215], v220 offset:128
	s_waitcnt lgkmcnt(8)
	s_mov_b32 m0, s75
	v_mfma_f32_32x32x16_bf16 v[18:33], v[216:219], v[46:49], v[18:33]
	global_load_lds_dwordx4 v254, s[36:37]
	ds_read_b128 v[216:219], v220 offset:8320
	s_waitcnt lgkmcnt(8)
	s_mov_b32 m0, s101
	v_mfma_f32_32x32x16_bf16 v[2:17], v[226:229], v[46:49], v[2:17]
	global_load_lds_dwordx4 v254, s[36:37] offset:128
	ds_read_b128 v[226:229], v195
	s_waitcnt lgkmcnt(8)
	v_mfma_f32_32x32x16_bf16 v[18:33], v[230:233], v[50:53], v[18:33]
	ds_read_b128 v[230:233], v195 offset:1024
	s_waitcnt lgkmcnt(8)
	v_mfma_f32_32x32x16_bf16 v[2:17], v[234:237], v[50:53], v[2:17]
	s_waitcnt lgkmcnt(7)
	v_mfma_f32_32x32x16_bf16 v[18:33], v[196:199], v[54:57], v[18:33]
	s_waitcnt lgkmcnt(6)
	v_mfma_f32_32x32x16_bf16 v[2:17], v[200:203], v[54:57], v[2:17]
	s_waitcnt lgkmcnt(1)
	v_mfma_f32_32x32x16_bf16 v[18:33], v[204:207], v[226:229], v[18:33]
	v_mfma_f32_32x32x16_bf16 v[2:17], v[208:211], v[226:229], v[2:17]
	s_waitcnt lgkmcnt(0)
	v_mfma_f32_32x32x16_bf16 v[18:33], v[212:215], v[230:233], v[18:33]
	s_add_i32 s36, s79, 0x7f
	s_cmp_le_u32 s36, s59
	v_mfma_f32_32x32x16_bf16 v[2:17], v[216:219], v[230:233], v[2:17]
	s_branch .Lqk1_join
.LBB0_194:
	v_ashrrev_i32_e32 v193, 5, v192
	v_and_b32_e32 v194, 31, v192
	v_lshlrev_b32_e32 v195, 4, v192
	v_lshlrev_b32_e32 v221, 4, v193
	v_lshlrev_b32_e32 v220, 8, v194
	s_add_i32 s36, s79, 0x7f
	s_cmp_le_u32 s36, s59
	v_bitop3_b32 v2, v195, v221, s48 bitop3:0x6c
	v_add3_u32 v6, s85, v2, v220
	v_xor_b32_e32 v250, 32, v6
	v_xor_b32_e32 v222, 64, v6
	v_xor_b32_e32 v220, 0x60, v6
	v_add_u32_e32 v195, s81, v195
	ds_read_b128 v[2:5], v6
	ds_read_b128 v[196:199], v6 offset:8192
	ds_read_b128 v[200:203], v250
	ds_read_b128 v[204:207], v250 offset:8192
	ds_read_b128 v[208:211], v222
	ds_read_b128 v[212:215], v222 offset:8192
	ds_read_b128 v[216:219], v220
	ds_read_b128 v[226:229], v220 offset:8192
	ds_read_b128 v[230:233], v6 offset:128
	ds_read_b128 v[234:237], v6 offset:8320
	s_waitcnt lgkmcnt(9)
	v_mfma_f32_32x32x16_bf16 v[18:33], v[2:5], v[34:37], 0
	s_waitcnt lgkmcnt(8)
	v_mfma_f32_32x32x16_bf16 v[2:17], v[196:199], v[34:37], 0
	ds_read_b128 v[196:199], v250 offset:128
	s_waitcnt lgkmcnt(8)
	v_mfma_f32_32x32x16_bf16 v[18:33], v[200:203], v[38:41], v[18:33]
	ds_read_b128 v[200:203], v250 offset:8320
	s_waitcnt lgkmcnt(8)
	v_mfma_f32_32x32x16_bf16 v[2:17], v[204:207], v[38:41], v[2:17]
	ds_read_b128 v[204:207], v222 offset:128
	s_waitcnt lgkmcnt(8)
	v_mfma_f32_32x32x16_bf16 v[18:33], v[208:211], v[42:45], v[18:33]
	ds_read_b128 v[208:211], v222 offset:8320
	s_waitcnt lgkmcnt(8)
	v_mfma_f32_32x32x16_bf16 v[2:17], v[212:215], v[42:45], v[2:17]
	ds_read_b128 v[212:215], v220 offset:128
	s_waitcnt lgkmcnt(8)
	v_mfma_f32_32x32x16_bf16 v[18:33], v[216:219], v[46:49], v[18:33]
	ds_read_b128 v[216:219], v220 offset:8320
	s_waitcnt lgkmcnt(8)
	v_mfma_f32_32x32x16_bf16 v[2:17], v[226:229], v[46:49], v[2:17]
	ds_read_b128 v[226:229], v195
	s_waitcnt lgkmcnt(8)
	v_mfma_f32_32x32x16_bf16 v[18:33], v[230:233], v[50:53], v[18:33]
	ds_read_b128 v[230:233], v195 offset:1024
	s_waitcnt lgkmcnt(8)
	v_mfma_f32_32x32x16_bf16 v[2:17], v[234:237], v[50:53], v[2:17]
	s_waitcnt lgkmcnt(7)
	v_mfma_f32_32x32x16_bf16 v[18:33], v[196:199], v[54:57], v[18:33]
	s_waitcnt lgkmcnt(6)
	v_mfma_f32_32x32x16_bf16 v[2:17], v[200:203], v[54:57], v[2:17]
	s_waitcnt lgkmcnt(1)
	v_mfma_f32_32x32x16_bf16 v[18:33], v[204:207], v[226:229], v[18:33]
	v_mfma_f32_32x32x16_bf16 v[2:17], v[208:211], v[226:229], v[2:17]
	s_waitcnt lgkmcnt(0)
	v_mfma_f32_32x32x16_bf16 v[18:33], v[212:215], v[230:233], v[18:33]
	v_mfma_f32_32x32x16_bf16 v[2:17], v[216:219], v[230:233], v[2:17]
